# GEMM k-loops P6/P8/P11/P15/P17: LDS-write stage waits only for its own register set (vmcnt +8) when the younger set is in flight
# speedup vs baseline: 1.0097x; 1.0097x over previous
.LBB0_1721:
	s_or_b64 exec, exec, s[20:21]
	v_add_u32_e32 v4, s35, v158
	v_ashrrev_i32_e32 v5, 31, v4
	v_lshlrev_b64 v[4:5], 11, v[4:5]
	v_lshl_add_u64 v[140:141], s[82:83], 0, v[4:5]
	v_add_u32_e32 v4, s35, v159
	v_ashrrev_i32_e32 v5, 31, v4
	v_lshlrev_b64 v[4:5], 11, v[4:5]
	v_lshl_add_u64 v[144:145], s[82:83], 0, v[4:5]
	v_add_u32_e32 v4, s35, v160
	v_ashrrev_i32_e32 v5, 31, v4
	v_lshlrev_b64 v[4:5], 11, v[4:5]
	v_lshl_add_u64 v[148:149], s[82:83], 0, v[4:5]
	v_add_u32_e32 v4, s35, v1
	v_ashrrev_i32_e32 v5, 31, v4
	v_lshlrev_b64 v[4:5], 11, v[4:5]
	v_lshl_add_u64 v[138:139], s[82:83], 0, v[48:49]
	v_lshl_add_u64 v[142:143], s[82:83], 0, v[42:43]
	v_lshl_add_u64 v[146:147], s[82:83], 0, v[36:37]
	v_lshl_add_u64 v[150:151], s[82:83], 0, v[34:35]
	v_lshl_add_u64 v[152:153], s[82:83], 0, v[4:5]
	s_mov_b32 s37, 0
	v_mov_b32_e32 v3, v2
	v_mov_b32_e32 v4, v2
	v_mov_b32_e32 v5, v2
	v_mov_b32_e32 v6, v2
	v_mov_b32_e32 v7, v2
	v_mov_b32_e32 v8, v2
	v_mov_b32_e32 v9, v2
	v_mov_b32_e32 v10, v2
	v_mov_b32_e32 v11, v2
	v_mov_b32_e32 v12, v2
	v_mov_b32_e32 v13, v2
	v_mov_b32_e32 v14, v2
	v_mov_b32_e32 v15, v2
	v_mov_b32_e32 v16, v2
	v_mov_b32_e32 v17, v2
	v_mov_b32_e32 v18, v2
	v_mov_b32_e32 v19, v2
	v_mov_b32_e32 v20, v2
	v_mov_b32_e32 v21, v2
	v_mov_b32_e32 v22, v2
	v_mov_b32_e32 v23, v2
	v_mov_b32_e32 v24, v2
	v_mov_b32_e32 v25, v2
	v_mov_b32_e32 v26, v2
	v_mov_b32_e32 v27, v2
	v_mov_b32_e32 v28, v2
	v_mov_b32_e32 v29, v2
	v_mov_b32_e32 v30, v2
	v_mov_b32_e32 v31, v2
	v_mov_b32_e32 v32, v2
	v_mov_b32_e32 v33, v2
	v_mov_b32_e32 v34, v2
	v_mov_b32_e32 v35, v2
	v_mov_b32_e32 v36, v2
	v_mov_b32_e32 v37, v2
	v_mov_b32_e32 v38, v2
	v_mov_b32_e32 v39, v2
	v_mov_b32_e32 v40, v2
	v_mov_b32_e32 v41, v2
	v_mov_b32_e32 v42, v2
	v_mov_b32_e32 v43, v2
	v_mov_b32_e32 v44, v2
	v_mov_b32_e32 v45, v2
	v_mov_b32_e32 v46, v2
	v_mov_b32_e32 v47, v2
	v_mov_b32_e32 v48, v2
	v_mov_b32_e32 v49, v2
	v_mov_b32_e32 v50, v2
	v_mov_b32_e32 v51, v2
	v_mov_b32_e32 v52, v2
	v_mov_b32_e32 v53, v2
	v_mov_b32_e32 v54, v2
	v_mov_b32_e32 v55, v2
	v_mov_b32_e32 v56, v2
	v_mov_b32_e32 v57, v2
	v_mov_b32_e32 v58, v2
	v_mov_b32_e32 v59, v2
	v_mov_b32_e32 v60, v2
	v_mov_b32_e32 v61, v2
	v_mov_b32_e32 v62, v2
	v_mov_b32_e32 v63, v2
	v_mov_b32_e32 v64, v2
	v_mov_b32_e32 v65, v2
	s_waitcnt lgkmcnt(0)
	s_barrier
	ds_read_b128 v[192:195], v161 offset:0
	ds_read_b128 v[196:199], v162 offset:18432
	ds_read_b128 v[200:203], v162 offset:23040
	ds_read_b128 v[204:207], v161 offset:4608
	ds_read_b128 v[208:211], v161 offset:32
	ds_read_b128 v[212:215], v162 offset:18464
	ds_read_b128 v[216:219], v162 offset:23072
	ds_read_b128 v[220:223], v161 offset:4640
	v_subrev_u32_e32 v152, s82, v152
	v_add_u32_e32 v152, v152, v136
	v_subrev_u32_e32 v150, s82, v150
	v_add_u32_e32 v150, v150, v136
	v_subrev_u32_e32 v148, s82, v148
	v_add_u32_e32 v148, v148, v136
	v_subrev_u32_e32 v146, s82, v146
	v_add_u32_e32 v146, v146, v136
	v_subrev_u32_e32 v144, s82, v144
	v_add_u32_e32 v144, v144, v136
	v_subrev_u32_e32 v142, s82, v142
	v_add_u32_e32 v142, v142, v136
	v_subrev_u32_e32 v140, s82, v140
	v_add_u32_e32 v140, v140, v136
	v_subrev_u32_e32 v138, s82, v138
	v_add_u32_e32 v138, v138, v136
	s_add_u32 s84, s82, 0xa380000
	s_addc_u32 s85, s83, 0
	s_add_u32 s86, s82, 0x89c0000
	s_addc_u32 s87, s83, 0
	s_and_b64 s[88:89], exec, s[10:11]
	s_cselect_b32 s90, 1, 0
	s_and_b64 s[88:89], exec, s[4:5]
	s_cselect_b32 s91, 1, 0
	s_and_b32 s90, s90, s91
	s_and_b64 s[88:89], exec, s[6:7]
	s_cselect_b32 s91, 1, 0
	s_and_b32 s90, s90, s91
	s_and_b64 s[88:89], exec, s[8:9]
	s_cselect_b32 s91, 1, 0
	s_and_b32 s90, s90, s91
	s_branch .LBB0_1724

.LBB0_1724:
	s_cmp_gt_u32 s37, 12
	s_cbranch_scc1 .Lgw1_sa
	s_cmp_eq_u32 s90, 0
	s_cbranch_scc1 .Lgw1_sa0
	s_waitcnt vmcnt(11)
	ds_write_b128 v154, v[66:69] offset:36864
	ds_write_b128 v154, v[70:73] offset:55296
	s_waitcnt vmcnt(10)
	ds_write_b128 v154, v[78:81] offset:41472
	ds_write_b128 v154, v[74:77] offset:59904
	s_waitcnt vmcnt(9)
	ds_write_b128 v154, v[82:85] offset:46080
	ds_write_b128 v154, v[90:93] offset:64512
	s_waitcnt vmcnt(8)
	ds_write_b128 v154, v[102:105] offset:50688
	ds_write_b128 v156, v[106:109] offset:13824
	s_branch .Lgw1_la

.Lgw1_sa:
	s_waitcnt vmcnt(3)
	ds_write_b128 v154, v[66:69] offset:36864
	ds_write_b128 v154, v[70:73] offset:55296
	s_waitcnt vmcnt(2)
	ds_write_b128 v154, v[78:81] offset:41472
	ds_write_b128 v154, v[74:77] offset:59904
	s_waitcnt vmcnt(1)
	ds_write_b128 v154, v[82:85] offset:46080
	ds_write_b128 v154, v[90:93] offset:64512
	s_waitcnt vmcnt(0)
	ds_write_b128 v154, v[102:105] offset:50688
	ds_write_b128 v156, v[106:109] offset:13824
	s_cbranch_scc1 .LBB0_1734
.Lgw1_la:
	global_load_dwordx4 v[66:69], v152, s[84:85] offset:384
	s_and_saveexec_b64 s[20:21], s[4:5]
	s_cbranch_execz .LBB0_1727
	global_load_dwordx4 v[70:73], v150, s[86:87] offset:384

.LBB0_1734:
	s_cmp_gt_u32 s37, 13
	s_cselect_b64 s[20:21], -1, 0
	s_and_b64 vcc, exec, s[20:21]
	s_waitcnt lgkmcnt(4)
	v_mfma_f32_32x32x16_bf16 v[50:65], v[192:195], v[196:199], v[50:65]
	v_mfma_f32_32x32x16_bf16 v[34:49], v[192:195], v[200:203], v[34:49]
	v_mfma_f32_32x32x16_bf16 v[18:33], v[204:207], v[196:199], v[18:33]
	v_mfma_f32_32x32x16_bf16 v[2:17], v[204:207], v[200:203], v[2:17]
	ds_read_b128 v[164:167], v161 offset:64
	ds_read_b128 v[168:171], v162 offset:18496
	ds_read_b128 v[172:175], v162 offset:23104
	ds_read_b128 v[176:179], v161 offset:4672
	s_waitcnt lgkmcnt(4)
	v_mfma_f32_32x32x16_bf16 v[50:65], v[208:211], v[212:215], v[50:65]
	v_mfma_f32_32x32x16_bf16 v[34:49], v[208:211], v[216:219], v[34:49]
	v_mfma_f32_32x32x16_bf16 v[18:33], v[220:223], v[212:215], v[18:33]
	v_mfma_f32_32x32x16_bf16 v[2:17], v[220:223], v[216:219], v[2:17]
	ds_read_b128 v[180:183], v161 offset:96
	ds_read_b128 v[184:187], v162 offset:18528
	ds_read_b128 v[188:191], v162 offset:23136
	ds_read_b128 v[224:227], v161 offset:4704
	s_waitcnt lgkmcnt(4)
	v_mfma_f32_32x32x16_bf16 v[50:65], v[164:167], v[168:171], v[50:65]
	v_mfma_f32_32x32x16_bf16 v[34:49], v[164:167], v[172:175], v[34:49]
	s_waitcnt lgkmcnt(0)
	s_barrier
	ds_read_b128 v[192:195], v161 offset:36864
	ds_read_b128 v[196:199], v162 offset:55296
	ds_read_b128 v[200:203], v162 offset:59904
	ds_read_b128 v[204:207], v161 offset:41472
	ds_read_b128 v[208:211], v161 offset:36896
	ds_read_b128 v[212:215], v162 offset:55328
	ds_read_b128 v[216:219], v162 offset:59936
	ds_read_b128 v[220:223], v161 offset:41504
	v_mfma_f32_32x32x16_bf16 v[18:33], v[176:179], v[168:171], v[18:33]
	v_mfma_f32_32x32x16_bf16 v[2:17], v[176:179], v[172:175], v[2:17]
	v_mfma_f32_32x32x16_bf16 v[50:65], v[180:183], v[184:187], v[50:65]
	v_mfma_f32_32x32x16_bf16 v[34:49], v[180:183], v[188:191], v[34:49]
	v_mfma_f32_32x32x16_bf16 v[18:33], v[224:227], v[184:187], v[18:33]
	v_mfma_f32_32x32x16_bf16 v[2:17], v[224:227], v[188:191], v[2:17]
	s_cbranch_vccnz .LBB0_1723
	s_cmp_gt_u32 s37, 11
	s_cbranch_scc1 .Lgw1_sb
	s_cmp_eq_u32 s90, 0
	s_cbranch_scc1 .Lgw1_sb0
	s_waitcnt vmcnt(11)
	ds_write_b128 v154, v[86:89]
	ds_write_b128 v154, v[94:97] offset:18432
	s_waitcnt vmcnt(10)
	ds_write_b128 v154, v[110:113] offset:4608
	ds_write_b128 v154, v[98:101] offset:23040
	s_waitcnt vmcnt(9)
	ds_write_b128 v154, v[114:117] offset:9216
	ds_write_b128 v154, v[118:121] offset:27648
	s_waitcnt vmcnt(8)
	ds_write_b128 v154, v[122:125] offset:13824
	ds_write_b128 v154, v[126:129] offset:32256
	s_branch .Lgw1_lb
.Lgw1_sb0:
	s_cmp_gt_u32 s37, 11
.Lgw1_sb:
	s_waitcnt vmcnt(3)
	ds_write_b128 v154, v[86:89]
	ds_write_b128 v154, v[94:97] offset:18432
	s_waitcnt vmcnt(2)
	ds_write_b128 v154, v[110:113] offset:4608
	ds_write_b128 v154, v[98:101] offset:23040
	s_waitcnt vmcnt(1)
	ds_write_b128 v154, v[114:117] offset:9216
	ds_write_b128 v154, v[118:121] offset:27648
	s_waitcnt vmcnt(0)
	ds_write_b128 v154, v[122:125] offset:13824
	ds_write_b128 v154, v[126:129] offset:32256
	s_cbranch_scc1 .LBB0_1723
.Lgw1_lb:
	global_load_dwordx4 v[86:89], v152, s[84:85] offset:512
	s_and_saveexec_b64 s[22:23], s[4:5]
	s_cbranch_execz .LBB0_1738
	global_load_dwordx4 v[94:97], v150, s[86:87] offset:512

.LBB0_1920:
	s_or_b64 exec, exec, s[2:3]
	v_add_u32_e32 v2, s33, v194
	v_ashrrev_i32_e32 v3, 31, v2
	v_lshlrev_b64 v[2:3], 11, v[2:3]
	v_lshl_add_u64 v[168:169], s[82:83], 0, v[2:3]
	v_add_u32_e32 v2, s33, v195
	v_ashrrev_i32_e32 v3, 31, v2
	v_lshlrev_b64 v[2:3], 11, v[2:3]
	v_lshl_add_u64 v[172:173], s[82:83], 0, v[2:3]
	v_add_u32_e32 v2, s33, v196
	v_ashrrev_i32_e32 v3, 31, v2
	v_lshlrev_b64 v[2:3], 11, v[2:3]
	v_lshl_add_u64 v[176:177], s[82:83], 0, v[2:3]
	v_add_u32_e32 v2, s33, v1
	v_ashrrev_i32_e32 v3, 31, v2
	v_lshlrev_b64 v[2:3], 11, v[2:3]
	v_lshl_add_u64 v[166:167], s[82:83], 0, v[48:49]
	v_lshl_add_u64 v[170:171], s[82:83], 0, v[42:43]
	v_lshl_add_u64 v[174:175], s[82:83], 0, v[36:37]
	v_lshl_add_u64 v[178:179], s[82:83], 0, v[34:35]
	v_lshl_add_u64 v[180:181], s[82:83], 0, v[2:3]
	s_mov_b32 s35, 0
	v_mov_b32_e32 v51, v50
	v_mov_b32_e32 v52, v50
	v_mov_b32_e32 v53, v50
	v_mov_b32_e32 v54, v50
	v_mov_b32_e32 v55, v50
	v_mov_b32_e32 v56, v50
	v_mov_b32_e32 v57, v50
	v_mov_b32_e32 v58, v50
	v_mov_b32_e32 v59, v50
	v_mov_b32_e32 v60, v50
	v_mov_b32_e32 v61, v50
	v_mov_b32_e32 v62, v50
	v_mov_b32_e32 v63, v50
	v_mov_b32_e32 v64, v50
	v_mov_b32_e32 v65, v50
	v_mov_b32_e32 v34, v50
	v_mov_b32_e32 v35, v50
	v_mov_b32_e32 v36, v50
	v_mov_b32_e32 v37, v50
	v_mov_b32_e32 v38, v50
	v_mov_b32_e32 v39, v50
	v_mov_b32_e32 v40, v50
	v_mov_b32_e32 v41, v50
	v_mov_b32_e32 v42, v50
	v_mov_b32_e32 v43, v50
	v_mov_b32_e32 v44, v50
	v_mov_b32_e32 v45, v50
	v_mov_b32_e32 v46, v50
	v_mov_b32_e32 v47, v50
	v_mov_b32_e32 v48, v50
	v_mov_b32_e32 v49, v50
	v_mov_b32_e32 v18, v50
	v_mov_b32_e32 v19, v50
	v_mov_b32_e32 v20, v50
	v_mov_b32_e32 v21, v50
	v_mov_b32_e32 v22, v50
	v_mov_b32_e32 v23, v50
	v_mov_b32_e32 v24, v50
	v_mov_b32_e32 v25, v50
	v_mov_b32_e32 v26, v50
	v_mov_b32_e32 v27, v50
	v_mov_b32_e32 v28, v50
	v_mov_b32_e32 v29, v50
	v_mov_b32_e32 v30, v50
	v_mov_b32_e32 v31, v50
	v_mov_b32_e32 v32, v50
	v_mov_b32_e32 v33, v50
	v_mov_b32_e32 v2, v50
	v_mov_b32_e32 v3, v50
	v_mov_b32_e32 v4, v50
	v_mov_b32_e32 v5, v50
	v_mov_b32_e32 v6, v50
	v_mov_b32_e32 v7, v50
	v_mov_b32_e32 v8, v50
	v_mov_b32_e32 v9, v50
	v_mov_b32_e32 v10, v50
	v_mov_b32_e32 v11, v50
	v_mov_b32_e32 v12, v50
	v_mov_b32_e32 v13, v50
	v_mov_b32_e32 v14, v50
	v_mov_b32_e32 v15, v50
	v_mov_b32_e32 v16, v50
	v_mov_b32_e32 v17, v50
	s_waitcnt lgkmcnt(0)
	s_barrier
	ds_read_b128 v[206:209], v203 offset:0
	ds_read_b128 v[210:213], v204 offset:18432
	ds_read_b128 v[214:217], v204 offset:23040
	ds_read_b128 v[218:221], v203 offset:4608
	ds_read_b128 v[222:225], v203 offset:32
	ds_read_b128 v[226:229], v204 offset:18464
	ds_read_b128 v[230:233], v204 offset:23072
	ds_read_b128 v[234:237], v203 offset:4640
	v_subrev_u32_e32 v180, s82, v180
	v_add_u32_e32 v180, v180, v138
	v_subrev_u32_e32 v178, s82, v178
	v_add_u32_e32 v178, v178, v138
	v_subrev_u32_e32 v176, s82, v176
	v_add_u32_e32 v176, v176, v138
	v_subrev_u32_e32 v174, s82, v174
	v_add_u32_e32 v174, v174, v138
	v_subrev_u32_e32 v172, s82, v172
	v_add_u32_e32 v172, v172, v138
	v_subrev_u32_e32 v170, s82, v170
	v_add_u32_e32 v170, v170, v138
	v_subrev_u32_e32 v168, s82, v168
	v_add_u32_e32 v168, v168, v138
	v_subrev_u32_e32 v166, s82, v166
	v_add_u32_e32 v166, v166, v138
	s_add_u32 s84, s82, 0xc4c0000
	s_addc_u32 s85, s83, 0
	s_add_u32 s86, s82, 0x99d0000
	s_addc_u32 s87, s83, 0
	s_and_b64 s[88:89], exec, s[12:13]
	s_cselect_b32 s90, 1, 0
	s_and_b64 s[88:89], exec, s[14:15]
	s_cselect_b32 s91, 1, 0
	s_and_b32 s90, s90, s91
	s_and_b64 s[88:89], exec, s[16:17]
	s_cselect_b32 s91, 1, 0
	s_and_b32 s90, s90, s91
	s_and_b64 s[88:89], exec, s[18:19]
	s_cselect_b32 s91, 1, 0
	s_and_b32 s90, s90, s91
	s_branch .LBB0_1923

.LBB0_1923:
	s_cmp_gt_u32 s35, 12
	s_cbranch_scc1 .Lgw2_sa
	s_cmp_eq_u32 s90, 0
	s_cbranch_scc1 .Lgw2_sa0
	s_waitcnt vmcnt(11)
	ds_write_b128 v137, v[66:69] offset:36864
	ds_write_b128 v137, v[70:73] offset:55296
	s_waitcnt vmcnt(10)
	ds_write_b128 v137, v[78:81] offset:41472
	ds_write_b128 v137, v[74:77] offset:59904
	s_waitcnt vmcnt(9)
	ds_write_b128 v137, v[82:85] offset:46080
	ds_write_b128 v137, v[90:93] offset:64512
	s_waitcnt vmcnt(8)
	ds_write_b128 v137, v[102:105] offset:50688
	ds_write_b128 v183, v[106:109] offset:13824
	s_branch .Lgw2_la

.Lgw2_sa:
	s_waitcnt vmcnt(3)
	ds_write_b128 v137, v[66:69] offset:36864
	ds_write_b128 v137, v[70:73] offset:55296
	s_waitcnt vmcnt(2)
	ds_write_b128 v137, v[78:81] offset:41472
	ds_write_b128 v137, v[74:77] offset:59904
	s_waitcnt vmcnt(1)
	ds_write_b128 v137, v[82:85] offset:46080
	ds_write_b128 v137, v[90:93] offset:64512
	s_waitcnt vmcnt(0)
	ds_write_b128 v137, v[102:105] offset:50688
	ds_write_b128 v183, v[106:109] offset:13824
	s_cbranch_scc1 .LBB0_1933
.Lgw2_la:
	global_load_dwordx4 v[66:69], v180, s[84:85] offset:384
	s_and_saveexec_b64 s[2:3], s[12:13]
	s_cbranch_execz .LBB0_1926
	global_load_dwordx4 v[70:73], v178, s[86:87] offset:384

.LBB0_1933:
	s_cmp_gt_u32 s35, 13
	s_cselect_b64 s[2:3], -1, 0
	s_and_b64 vcc, exec, s[2:3]
	s_waitcnt lgkmcnt(4)
	v_mfma_f32_32x32x16_bf16 v[50:65], v[206:209], v[210:213], v[50:65]
	v_mfma_f32_32x32x16_bf16 v[34:49], v[206:209], v[214:217], v[34:49]
	v_mfma_f32_32x32x16_bf16 v[18:33], v[218:221], v[210:213], v[18:33]
	v_mfma_f32_32x32x16_bf16 v[2:17], v[218:221], v[214:217], v[2:17]
	ds_read_b128 v[206:209], v203 offset:64
	ds_read_b128 v[210:213], v204 offset:18496
	ds_read_b128 v[214:217], v204 offset:23104
	ds_read_b128 v[218:221], v203 offset:4672
	s_waitcnt lgkmcnt(4)
	v_mfma_f32_32x32x16_bf16 v[50:65], v[222:225], v[226:229], v[50:65]
	v_mfma_f32_32x32x16_bf16 v[34:49], v[222:225], v[230:233], v[34:49]
	v_mfma_f32_32x32x16_bf16 v[18:33], v[234:237], v[226:229], v[18:33]
	v_mfma_f32_32x32x16_bf16 v[2:17], v[234:237], v[230:233], v[2:17]
	ds_read_b128 v[222:225], v203 offset:96
	ds_read_b128 v[226:229], v204 offset:18528
	ds_read_b128 v[230:233], v204 offset:23136
	ds_read_b128 v[234:237], v203 offset:4704
	s_waitcnt lgkmcnt(4)
	v_mfma_f32_32x32x16_bf16 v[50:65], v[206:209], v[210:213], v[50:65]
	v_mfma_f32_32x32x16_bf16 v[34:49], v[206:209], v[214:217], v[34:49]
	s_waitcnt lgkmcnt(0)
	s_barrier
	v_mfma_f32_32x32x16_bf16 v[18:33], v[218:221], v[210:213], v[18:33]
	v_mfma_f32_32x32x16_bf16 v[2:17], v[218:221], v[214:217], v[2:17]
	ds_read_b128 v[206:209], v203 offset:36864
	ds_read_b128 v[210:213], v204 offset:55296
	ds_read_b128 v[214:217], v204 offset:59904
	ds_read_b128 v[218:221], v203 offset:41472
	v_mfma_f32_32x32x16_bf16 v[50:65], v[222:225], v[226:229], v[50:65]
	v_mfma_f32_32x32x16_bf16 v[34:49], v[222:225], v[230:233], v[34:49]
	v_mfma_f32_32x32x16_bf16 v[18:33], v[234:237], v[226:229], v[18:33]
	v_mfma_f32_32x32x16_bf16 v[2:17], v[234:237], v[230:233], v[2:17]
	ds_read_b128 v[222:225], v203 offset:36896
	ds_read_b128 v[226:229], v204 offset:55328
	ds_read_b128 v[230:233], v204 offset:59936
	ds_read_b128 v[234:237], v203 offset:41504
	s_cbranch_vccnz .LBB0_1922
	s_cmp_gt_u32 s35, 11
	s_cbranch_scc1 .Lgw2_sb
	s_cmp_eq_u32 s90, 0
	s_cbranch_scc1 .Lgw2_sb0
	s_waitcnt vmcnt(11)
	ds_write_b128 v137, v[86:89]
	ds_write_b128 v137, v[94:97] offset:18432
	s_waitcnt vmcnt(10)
	ds_write_b128 v137, v[110:113] offset:4608
	ds_write_b128 v137, v[98:101] offset:23040
	s_waitcnt vmcnt(9)
	ds_write_b128 v137, v[114:117] offset:9216
	ds_write_b128 v137, v[118:121] offset:27648
	s_waitcnt vmcnt(8)
	ds_write_b128 v137, v[122:125] offset:13824
	ds_write_b128 v137, v[126:129] offset:32256
	s_branch .Lgw2_lb
.Lgw2_sb0:
	s_cmp_gt_u32 s35, 11
.Lgw2_sb:
	s_waitcnt vmcnt(3)
	ds_write_b128 v137, v[86:89]
	ds_write_b128 v137, v[94:97] offset:18432
	s_waitcnt vmcnt(2)
	ds_write_b128 v137, v[110:113] offset:4608
	ds_write_b128 v137, v[98:101] offset:23040
	s_waitcnt vmcnt(1)
	ds_write_b128 v137, v[114:117] offset:9216
	ds_write_b128 v137, v[118:121] offset:27648
	s_waitcnt vmcnt(0)
	ds_write_b128 v137, v[122:125] offset:13824
	ds_write_b128 v137, v[126:129] offset:32256
	s_cbranch_scc1 .LBB0_1922
.Lgw2_lb:
	global_load_dwordx4 v[86:89], v180, s[84:85] offset:512
	s_and_saveexec_b64 s[36:37], s[12:13]
	s_cbranch_execz .LBB0_1937
	global_load_dwordx4 v[94:97], v178, s[86:87] offset:512

.LBB0_2250:
	s_or_b64 exec, exec, s[2:3]
	v_add_u32_e32 v4, s27, v180
	v_ashrrev_i32_e32 v5, 31, v4
	v_lshlrev_b64 v[4:5], 11, v[4:5]
	v_lshl_add_u64 v[146:147], s[82:83], 0, v[4:5]
	v_add_u32_e32 v4, s27, v181
	v_ashrrev_i32_e32 v5, 31, v4
	v_lshlrev_b64 v[4:5], 11, v[4:5]
	v_lshl_add_u64 v[154:155], s[82:83], 0, v[4:5]
	v_add_u32_e32 v4, s26, v1
	v_ashrrev_i32_e32 v5, 31, v4
	v_lshlrev_b64 v[4:5], 11, v[4:5]
	v_lshl_add_u64 v[156:157], s[82:83], 0, v[4:5]
	v_add_u32_e32 v4, s27, v1
	v_ashrrev_i32_e32 v5, 31, v4
	v_lshlrev_b64 v[4:5], 11, v[4:5]
	v_lshl_add_u64 v[144:145], s[82:83], 0, v[40:41]
	v_lshl_add_u64 v[148:149], s[82:83], 0, v[38:39]
	v_lshl_add_u64 v[150:151], s[82:83], 0, v[36:37]
	v_lshl_add_u64 v[152:153], s[82:83], 0, v[34:35]
	v_lshl_add_u64 v[158:159], s[82:83], 0, v[4:5]
	s_mov_b32 s13, 0
	v_mov_b32_e32 v3, v2
	v_mov_b32_e32 v4, v2
	v_mov_b32_e32 v5, v2
	v_mov_b32_e32 v6, v2
	v_mov_b32_e32 v7, v2
	v_mov_b32_e32 v8, v2
	v_mov_b32_e32 v9, v2
	v_mov_b32_e32 v10, v2
	v_mov_b32_e32 v11, v2
	v_mov_b32_e32 v12, v2
	v_mov_b32_e32 v13, v2
	v_mov_b32_e32 v14, v2
	v_mov_b32_e32 v15, v2
	v_mov_b32_e32 v16, v2
	v_mov_b32_e32 v17, v2
	v_mov_b32_e32 v18, v2
	v_mov_b32_e32 v19, v2
	v_mov_b32_e32 v20, v2
	v_mov_b32_e32 v21, v2
	v_mov_b32_e32 v22, v2
	v_mov_b32_e32 v23, v2
	v_mov_b32_e32 v24, v2
	v_mov_b32_e32 v25, v2
	v_mov_b32_e32 v26, v2
	v_mov_b32_e32 v27, v2
	v_mov_b32_e32 v28, v2
	v_mov_b32_e32 v29, v2
	v_mov_b32_e32 v30, v2
	v_mov_b32_e32 v31, v2
	v_mov_b32_e32 v32, v2
	v_mov_b32_e32 v33, v2
	v_mov_b32_e32 v34, v2
	v_mov_b32_e32 v35, v2
	v_mov_b32_e32 v36, v2
	v_mov_b32_e32 v37, v2
	v_mov_b32_e32 v38, v2
	v_mov_b32_e32 v39, v2
	v_mov_b32_e32 v40, v2
	v_mov_b32_e32 v41, v2
	v_mov_b32_e32 v42, v2
	v_mov_b32_e32 v43, v2
	v_mov_b32_e32 v44, v2
	v_mov_b32_e32 v45, v2
	v_mov_b32_e32 v46, v2
	v_mov_b32_e32 v47, v2
	v_mov_b32_e32 v48, v2
	v_mov_b32_e32 v49, v2
	v_mov_b32_e32 v50, v2
	v_mov_b32_e32 v51, v2
	v_mov_b32_e32 v52, v2
	v_mov_b32_e32 v53, v2
	v_mov_b32_e32 v54, v2
	v_mov_b32_e32 v55, v2
	v_mov_b32_e32 v56, v2
	v_mov_b32_e32 v57, v2
	v_mov_b32_e32 v58, v2
	v_mov_b32_e32 v59, v2
	v_mov_b32_e32 v60, v2
	v_mov_b32_e32 v61, v2
	v_mov_b32_e32 v62, v2
	v_mov_b32_e32 v63, v2
	v_mov_b32_e32 v64, v2
	v_mov_b32_e32 v65, v2
	s_waitcnt lgkmcnt(0)
	s_barrier
	ds_read_b128 v[212:215], v182 offset:18432
	ds_read_b128 v[216:219], v162 offset:0
	ds_read_b128 v[220:223], v182 offset:23040
	ds_read_b128 v[224:227], v162 offset:4608
	ds_read_b128 v[228:231], v182 offset:18464
	ds_read_b128 v[232:235], v162 offset:32
	ds_read_b128 v[236:239], v182 offset:23072
	ds_read_b128 v[240:243], v162 offset:4640
	v_subrev_u32_e32 v158, s82, v158
	v_add_u32_e32 v158, v158, v140
	v_subrev_u32_e32 v156, s82, v156
	v_add_u32_e32 v156, v156, v140
	v_subrev_u32_e32 v154, s82, v154
	v_add_u32_e32 v154, v154, v140
	v_subrev_u32_e32 v152, s82, v152
	v_add_u32_e32 v152, v152, v140
	v_subrev_u32_e32 v150, s82, v150
	v_add_u32_e32 v150, v150, v140
	v_subrev_u32_e32 v148, s82, v148
	v_add_u32_e32 v148, v148, v140
	v_subrev_u32_e32 v146, s82, v146
	v_add_u32_e32 v146, v146, v140
	v_subrev_u32_e32 v144, s82, v144
	v_add_u32_e32 v144, v144, v140
	s_add_u32 s84, s82, 0xa380000
	s_addc_u32 s85, s83, 0
	s_add_u32 s86, s82, 0x8bc0000
	s_addc_u32 s87, s83, 0
	s_and_b64 s[88:89], exec, s[6:7]
	s_cselect_b32 s90, 1, 0
	s_and_b64 s[88:89], exec, s[8:9]
	s_cselect_b32 s91, 1, 0
	s_and_b32 s90, s90, s91
	s_branch .LBB0_2253

.LBB0_2253:
	s_cmp_gt_u32 s13, 12
	s_cbranch_scc1 .Lgw3_sa
	s_cmp_eq_u32 s90, 0
	s_cbranch_scc1 .Lgw3_sa0
	s_waitcnt vmcnt(13)
	ds_write_b128 v160, v[66:69] offset:36864
	s_waitcnt vmcnt(12)
	ds_write_b128 v160, v[70:73] offset:55296
	s_waitcnt vmcnt(11)
	ds_write_b128 v160, v[74:77] offset:41472
	s_waitcnt vmcnt(10)
	ds_write_b128 v160, v[78:81] offset:59904
	s_waitcnt vmcnt(9)
	ds_write_b128 v160, v[82:85] offset:46080
	ds_write_b128 v160, v[86:89] offset:64512
	s_waitcnt vmcnt(8)
	ds_write_b128 v160, v[102:105] offset:50688
	ds_write_b128 v161, v[114:117] offset:13824
	s_branch .Lgw3_la

.Lgw3_sa:
	s_waitcnt vmcnt(5)
	ds_write_b128 v160, v[66:69] offset:36864
	s_waitcnt vmcnt(4)
	ds_write_b128 v160, v[70:73] offset:55296
	s_waitcnt vmcnt(3)
	ds_write_b128 v160, v[74:77] offset:41472
	s_waitcnt vmcnt(2)
	ds_write_b128 v160, v[78:81] offset:59904
	s_waitcnt vmcnt(1)
	ds_write_b128 v160, v[82:85] offset:46080
	ds_write_b128 v160, v[86:89] offset:64512
	s_waitcnt vmcnt(0)
	ds_write_b128 v160, v[102:105] offset:50688
	ds_write_b128 v161, v[114:117] offset:13824
	s_cbranch_scc1 .LBB0_2259
.Lgw3_la:
	global_load_dwordx4 v[66:69], v158, s[84:85] offset:384
	global_load_dwordx4 v[70:73], v156, s[86:87] offset:384
	v_mov_b32_e32 v131, v130
	global_load_dwordx4 v[74:77], v154, s[84:85] offset:384
	global_load_dwordx4 v[78:81], v152, s[86:87] offset:384
	global_load_dwordx4 v[82:85], v150, s[84:85] offset:384
	s_and_saveexec_b64 s[2:3], s[6:7]
	s_cbranch_execz .LBB0_2256
	global_load_dwordx4 v[86:89], v148, s[86:87] offset:384

.LBB0_2259:
	s_cmp_gt_u32 s13, 13
	s_cselect_b64 s[2:3], -1, 0
	s_and_b64 vcc, exec, s[2:3]
	s_waitcnt lgkmcnt(4)
	v_mfma_f32_32x32x16_bf16 v[50:65], v[212:215], v[216:219], v[50:65]
	v_mfma_f32_32x32x16_bf16 v[34:49], v[220:223], v[216:219], v[34:49]
	v_mfma_f32_32x32x16_bf16 v[18:33], v[212:215], v[224:227], v[18:33]
	v_mfma_f32_32x32x16_bf16 v[2:17], v[220:223], v[224:227], v[2:17]
	ds_read_b128 v[184:187], v182 offset:18496
	ds_read_b128 v[188:191], v162 offset:64
	ds_read_b128 v[192:195], v182 offset:23104
	ds_read_b128 v[196:199], v162 offset:4672
	s_waitcnt lgkmcnt(4)
	v_mfma_f32_32x32x16_bf16 v[50:65], v[228:231], v[232:235], v[50:65]
	v_mfma_f32_32x32x16_bf16 v[34:49], v[236:239], v[232:235], v[34:49]
	v_mfma_f32_32x32x16_bf16 v[18:33], v[228:231], v[240:243], v[18:33]
	v_mfma_f32_32x32x16_bf16 v[2:17], v[236:239], v[240:243], v[2:17]
	ds_read_b128 v[200:203], v182 offset:18528
	ds_read_b128 v[204:207], v162 offset:96
	ds_read_b128 v[208:211], v182 offset:23136
	ds_read_b128 v[248:251], v162 offset:4704
	s_waitcnt lgkmcnt(4)
	v_mfma_f32_32x32x16_bf16 v[50:65], v[184:187], v[188:191], v[50:65]
	v_mfma_f32_32x32x16_bf16 v[34:49], v[192:195], v[188:191], v[34:49]
	s_waitcnt lgkmcnt(0)
	s_barrier
	ds_read_b128 v[212:215], v182 offset:55296
	ds_read_b128 v[216:219], v162 offset:36864
	ds_read_b128 v[220:223], v182 offset:59904
	ds_read_b128 v[224:227], v162 offset:41472
	ds_read_b128 v[228:231], v182 offset:55328
	ds_read_b128 v[232:235], v162 offset:36896
	ds_read_b128 v[236:239], v182 offset:59936
	ds_read_b128 v[240:243], v162 offset:41504
	v_mfma_f32_32x32x16_bf16 v[18:33], v[184:187], v[196:199], v[18:33]
	v_mfma_f32_32x32x16_bf16 v[2:17], v[192:195], v[196:199], v[2:17]
	v_mfma_f32_32x32x16_bf16 v[50:65], v[200:203], v[204:207], v[50:65]
	v_mfma_f32_32x32x16_bf16 v[34:49], v[208:211], v[204:207], v[34:49]
	v_mfma_f32_32x32x16_bf16 v[18:33], v[200:203], v[248:251], v[18:33]
	v_mfma_f32_32x32x16_bf16 v[2:17], v[208:211], v[248:251], v[2:17]
	s_cbranch_vccnz .LBB0_2252
	s_cmp_gt_u32 s13, 11
	s_cbranch_scc1 .Lgw3_sb
	s_cmp_eq_u32 s90, 0
	s_cbranch_scc1 .Lgw3_sb0
	s_waitcnt vmcnt(13)
	ds_write_b128 v160, v[90:93]
	s_waitcnt vmcnt(12)
	ds_write_b128 v160, v[94:97] offset:18432
	s_waitcnt vmcnt(11)
	ds_write_b128 v160, v[98:101] offset:4608
	s_waitcnt vmcnt(10)
	ds_write_b128 v160, v[106:109] offset:23040
	s_waitcnt vmcnt(9)
	ds_write_b128 v160, v[110:113] offset:9216
	ds_write_b128 v160, v[118:121] offset:27648
	s_waitcnt vmcnt(8)
	ds_write_b128 v160, v[122:125] offset:13824
	ds_write_b128 v160, v[126:129] offset:32256
	s_branch .Lgw3_lb
.Lgw3_sb0:
	s_cmp_gt_u32 s13, 11
.Lgw3_sb:
	s_waitcnt vmcnt(5)
	ds_write_b128 v160, v[90:93]
	s_waitcnt vmcnt(4)
	ds_write_b128 v160, v[94:97] offset:18432
	s_waitcnt vmcnt(3)
	ds_write_b128 v160, v[98:101] offset:4608
	s_waitcnt vmcnt(2)
	ds_write_b128 v160, v[106:109] offset:23040
	s_waitcnt vmcnt(1)
	ds_write_b128 v160, v[110:113] offset:9216
	ds_write_b128 v160, v[118:121] offset:27648
	s_waitcnt vmcnt(0)
	ds_write_b128 v160, v[122:125] offset:13824
	ds_write_b128 v160, v[126:129] offset:32256
	s_cbranch_scc1 .LBB0_2252
.Lgw3_lb:
	global_load_dwordx4 v[90:93], v158, s[84:85] offset:512
	global_load_dwordx4 v[94:97], v156, s[86:87] offset:512
	v_mov_b32_e32 v131, v130
	global_load_dwordx4 v[98:101], v154, s[84:85] offset:512
	global_load_dwordx4 v[106:109], v152, s[86:87] offset:512
	global_load_dwordx4 v[110:113], v150, s[84:85] offset:512
	s_and_saveexec_b64 s[14:15], s[6:7]
	s_cbranch_execz .LBB0_2263
	global_load_dwordx4 v[118:121], v148, s[86:87] offset:512

.LBB0_2922:
	s_or_b64 exec, exec, s[20:21]
	v_add_u32_e32 v4, s35, v158
	v_ashrrev_i32_e32 v5, 31, v4
	v_lshlrev_b64 v[4:5], 12, v[4:5]
	v_lshl_add_u64 v[140:141], s[82:83], 0, v[4:5]
	v_add_u32_e32 v4, s35, v159
	v_ashrrev_i32_e32 v5, 31, v4
	v_lshlrev_b64 v[4:5], 12, v[4:5]
	v_lshl_add_u64 v[144:145], s[82:83], 0, v[4:5]
	v_add_u32_e32 v4, s35, v160
	v_ashrrev_i32_e32 v5, 31, v4
	v_lshlrev_b64 v[4:5], 12, v[4:5]
	v_lshl_add_u64 v[148:149], s[82:83], 0, v[4:5]
	v_add_u32_e32 v4, s35, v1
	v_ashrrev_i32_e32 v5, 31, v4
	v_lshlrev_b64 v[4:5], 12, v[4:5]
	v_lshl_add_u64 v[138:139], s[82:83], 0, v[48:49]
	v_lshl_add_u64 v[142:143], s[82:83], 0, v[42:43]
	v_lshl_add_u64 v[146:147], s[82:83], 0, v[36:37]
	v_lshl_add_u64 v[150:151], s[82:83], 0, v[34:35]
	v_lshl_add_u64 v[152:153], s[82:83], 0, v[4:5]
	s_mov_b32 s37, 0
	v_mov_b32_e32 v3, v2
	v_mov_b32_e32 v4, v2
	v_mov_b32_e32 v5, v2
	v_mov_b32_e32 v6, v2
	v_mov_b32_e32 v7, v2
	v_mov_b32_e32 v8, v2
	v_mov_b32_e32 v9, v2
	v_mov_b32_e32 v10, v2
	v_mov_b32_e32 v11, v2
	v_mov_b32_e32 v12, v2
	v_mov_b32_e32 v13, v2
	v_mov_b32_e32 v14, v2
	v_mov_b32_e32 v15, v2
	v_mov_b32_e32 v16, v2
	v_mov_b32_e32 v17, v2
	v_mov_b32_e32 v18, v2
	v_mov_b32_e32 v19, v2
	v_mov_b32_e32 v20, v2
	v_mov_b32_e32 v21, v2
	v_mov_b32_e32 v22, v2
	v_mov_b32_e32 v23, v2
	v_mov_b32_e32 v24, v2
	v_mov_b32_e32 v25, v2
	v_mov_b32_e32 v26, v2
	v_mov_b32_e32 v27, v2
	v_mov_b32_e32 v28, v2
	v_mov_b32_e32 v29, v2
	v_mov_b32_e32 v30, v2
	v_mov_b32_e32 v31, v2
	v_mov_b32_e32 v32, v2
	v_mov_b32_e32 v33, v2
	v_mov_b32_e32 v34, v2
	v_mov_b32_e32 v35, v2
	v_mov_b32_e32 v36, v2
	v_mov_b32_e32 v37, v2
	v_mov_b32_e32 v38, v2
	v_mov_b32_e32 v39, v2
	v_mov_b32_e32 v40, v2
	v_mov_b32_e32 v41, v2
	v_mov_b32_e32 v42, v2
	v_mov_b32_e32 v43, v2
	v_mov_b32_e32 v44, v2
	v_mov_b32_e32 v45, v2
	v_mov_b32_e32 v46, v2
	v_mov_b32_e32 v47, v2
	v_mov_b32_e32 v48, v2
	v_mov_b32_e32 v49, v2
	v_mov_b32_e32 v50, v2
	v_mov_b32_e32 v51, v2
	v_mov_b32_e32 v52, v2
	v_mov_b32_e32 v53, v2
	v_mov_b32_e32 v54, v2
	v_mov_b32_e32 v55, v2
	v_mov_b32_e32 v56, v2
	v_mov_b32_e32 v57, v2
	v_mov_b32_e32 v58, v2
	v_mov_b32_e32 v59, v2
	v_mov_b32_e32 v60, v2
	v_mov_b32_e32 v61, v2
	v_mov_b32_e32 v62, v2
	v_mov_b32_e32 v63, v2
	v_mov_b32_e32 v64, v2
	v_mov_b32_e32 v65, v2
	s_waitcnt lgkmcnt(0)
	s_barrier
	ds_read_b128 v[192:195], v161 offset:0
	ds_read_b128 v[196:199], v162 offset:18432
	ds_read_b128 v[200:203], v162 offset:23040
	ds_read_b128 v[204:207], v161 offset:4608
	ds_read_b128 v[208:211], v161 offset:32
	ds_read_b128 v[212:215], v162 offset:18464
	ds_read_b128 v[216:219], v162 offset:23072
	ds_read_b128 v[220:223], v161 offset:4640
	v_subrev_u32_e32 v152, s82, v152
	v_add_u32_e32 v152, v152, v136
	v_subrev_u32_e32 v150, s82, v150
	v_add_u32_e32 v150, v150, v136
	v_subrev_u32_e32 v148, s82, v148
	v_add_u32_e32 v148, v148, v136
	v_subrev_u32_e32 v146, s82, v146
	v_add_u32_e32 v146, v146, v136
	v_subrev_u32_e32 v144, s82, v144
	v_add_u32_e32 v144, v144, v136
	v_subrev_u32_e32 v142, s82, v142
	v_add_u32_e32 v142, v142, v136
	v_subrev_u32_e32 v140, s82, v140
	v_add_u32_e32 v140, v140, v136
	v_subrev_u32_e32 v138, s82, v138
	v_add_u32_e32 v138, v138, v136
	s_add_u32 s84, s82, 0x10740000
	s_addc_u32 s85, s83, 0
	s_add_u32 s86, s82, 0x95d0000
	s_addc_u32 s87, s83, 0
	s_and_b64 s[88:89], exec, s[10:11]
	s_cselect_b32 s90, 1, 0
	s_and_b64 s[88:89], exec, s[4:5]
	s_cselect_b32 s91, 1, 0
	s_and_b32 s90, s90, s91
	s_and_b64 s[88:89], exec, s[6:7]
	s_cselect_b32 s91, 1, 0
	s_and_b32 s90, s90, s91
	s_and_b64 s[88:89], exec, s[8:9]
	s_cselect_b32 s91, 1, 0
	s_and_b32 s90, s90, s91
	s_branch .LBB0_2925

.LBB0_2925:
	s_cmp_gt_u32 s37, 28
	s_cbranch_scc1 .Lgw4_sa
	s_cmp_eq_u32 s90, 0
	s_cbranch_scc1 .Lgw4_sa0
	s_waitcnt vmcnt(11)
	ds_write_b128 v154, v[66:69] offset:36864
	ds_write_b128 v154, v[70:73] offset:55296
	s_waitcnt vmcnt(10)
	ds_write_b128 v154, v[78:81] offset:41472
	ds_write_b128 v154, v[74:77] offset:59904
	s_waitcnt vmcnt(9)
	ds_write_b128 v154, v[82:85] offset:46080
	ds_write_b128 v154, v[90:93] offset:64512
	s_waitcnt vmcnt(8)
	ds_write_b128 v154, v[102:105] offset:50688
	ds_write_b128 v156, v[106:109] offset:13824
	s_branch .Lgw4_la

.LBB0_2935:
	s_cmp_gt_u32 s37, 29
	s_cselect_b64 s[20:21], -1, 0
	s_and_b64 vcc, exec, s[20:21]
	s_waitcnt lgkmcnt(4)
	v_mfma_f32_32x32x16_bf16 v[50:65], v[192:195], v[196:199], v[50:65]
	v_mfma_f32_32x32x16_bf16 v[34:49], v[192:195], v[200:203], v[34:49]
	v_mfma_f32_32x32x16_bf16 v[18:33], v[204:207], v[196:199], v[18:33]
	v_mfma_f32_32x32x16_bf16 v[2:17], v[204:207], v[200:203], v[2:17]
	ds_read_b128 v[164:167], v161 offset:64
	ds_read_b128 v[168:171], v162 offset:18496
	ds_read_b128 v[172:175], v162 offset:23104
	ds_read_b128 v[176:179], v161 offset:4672
	s_waitcnt lgkmcnt(4)
	v_mfma_f32_32x32x16_bf16 v[50:65], v[208:211], v[212:215], v[50:65]
	v_mfma_f32_32x32x16_bf16 v[34:49], v[208:211], v[216:219], v[34:49]
	v_mfma_f32_32x32x16_bf16 v[18:33], v[220:223], v[212:215], v[18:33]
	v_mfma_f32_32x32x16_bf16 v[2:17], v[220:223], v[216:219], v[2:17]
	ds_read_b128 v[180:183], v161 offset:96
	ds_read_b128 v[184:187], v162 offset:18528
	ds_read_b128 v[188:191], v162 offset:23136
	ds_read_b128 v[224:227], v161 offset:4704
	s_waitcnt lgkmcnt(4)
	v_mfma_f32_32x32x16_bf16 v[50:65], v[164:167], v[168:171], v[50:65]
	v_mfma_f32_32x32x16_bf16 v[34:49], v[164:167], v[172:175], v[34:49]
	s_waitcnt lgkmcnt(0)
	s_barrier
	ds_read_b128 v[192:195], v161 offset:36864
	ds_read_b128 v[196:199], v162 offset:55296
	ds_read_b128 v[200:203], v162 offset:59904
	ds_read_b128 v[204:207], v161 offset:41472
	ds_read_b128 v[208:211], v161 offset:36896
	ds_read_b128 v[212:215], v162 offset:55328
	ds_read_b128 v[216:219], v162 offset:59936
	ds_read_b128 v[220:223], v161 offset:41504
	v_mfma_f32_32x32x16_bf16 v[18:33], v[176:179], v[168:171], v[18:33]
	v_mfma_f32_32x32x16_bf16 v[2:17], v[176:179], v[172:175], v[2:17]
	v_mfma_f32_32x32x16_bf16 v[50:65], v[180:183], v[184:187], v[50:65]
	v_mfma_f32_32x32x16_bf16 v[34:49], v[180:183], v[188:191], v[34:49]
	v_mfma_f32_32x32x16_bf16 v[18:33], v[224:227], v[184:187], v[18:33]
	v_mfma_f32_32x32x16_bf16 v[2:17], v[224:227], v[188:191], v[2:17]
	s_cbranch_vccnz .LBB0_2924
	s_cmp_gt_u32 s37, 27
	s_cbranch_scc1 .Lgw4_sb
	s_cmp_eq_u32 s90, 0
	s_cbranch_scc1 .Lgw4_sb0
	s_waitcnt vmcnt(11)
	ds_write_b128 v154, v[86:89]
	ds_write_b128 v154, v[94:97] offset:18432
	s_waitcnt vmcnt(10)
	ds_write_b128 v154, v[110:113] offset:4608
	ds_write_b128 v154, v[98:101] offset:23040
	s_waitcnt vmcnt(9)
	ds_write_b128 v154, v[114:117] offset:9216
	ds_write_b128 v154, v[118:121] offset:27648
	s_waitcnt vmcnt(8)
	ds_write_b128 v154, v[122:125] offset:13824
	ds_write_b128 v154, v[126:129] offset:32256
	s_branch .Lgw4_lb
.Lgw4_sb0:
	s_cmp_gt_u32 s37, 27

.LBB0_3121:
	s_or_b64 exec, exec, s[2:3]
	v_add_u32_e32 v2, s33, v194
	v_ashrrev_i32_e32 v3, 31, v2
	v_lshlrev_b64 v[2:3], 11, v[2:3]
	v_lshl_add_u64 v[168:169], s[82:83], 0, v[2:3]
	v_add_u32_e32 v2, s33, v195
	v_ashrrev_i32_e32 v3, 31, v2
	v_lshlrev_b64 v[2:3], 11, v[2:3]
	v_lshl_add_u64 v[172:173], s[82:83], 0, v[2:3]
	v_add_u32_e32 v2, s33, v196
	v_ashrrev_i32_e32 v3, 31, v2
	v_lshlrev_b64 v[2:3], 11, v[2:3]
	v_lshl_add_u64 v[176:177], s[82:83], 0, v[2:3]
	v_add_u32_e32 v2, s33, v1
	v_ashrrev_i32_e32 v3, 31, v2
	v_lshlrev_b64 v[2:3], 11, v[2:3]
	v_lshl_add_u64 v[166:167], s[82:83], 0, v[48:49]
	v_lshl_add_u64 v[170:171], s[82:83], 0, v[42:43]
	v_lshl_add_u64 v[174:175], s[82:83], 0, v[36:37]
	v_lshl_add_u64 v[178:179], s[82:83], 0, v[34:35]
	v_lshl_add_u64 v[180:181], s[82:83], 0, v[2:3]
	s_mov_b32 s35, 0
	v_mov_b32_e32 v51, v50
	v_mov_b32_e32 v52, v50
	v_mov_b32_e32 v53, v50
	v_mov_b32_e32 v54, v50
	v_mov_b32_e32 v55, v50
	v_mov_b32_e32 v56, v50
	v_mov_b32_e32 v57, v50
	v_mov_b32_e32 v58, v50
	v_mov_b32_e32 v59, v50
	v_mov_b32_e32 v60, v50
	v_mov_b32_e32 v61, v50
	v_mov_b32_e32 v62, v50
	v_mov_b32_e32 v63, v50
	v_mov_b32_e32 v64, v50
	v_mov_b32_e32 v65, v50
	v_mov_b32_e32 v34, v50
	v_mov_b32_e32 v35, v50
	v_mov_b32_e32 v36, v50
	v_mov_b32_e32 v37, v50
	v_mov_b32_e32 v38, v50
	v_mov_b32_e32 v39, v50
	v_mov_b32_e32 v40, v50
	v_mov_b32_e32 v41, v50
	v_mov_b32_e32 v42, v50
	v_mov_b32_e32 v43, v50
	v_mov_b32_e32 v44, v50
	v_mov_b32_e32 v45, v50
	v_mov_b32_e32 v46, v50
	v_mov_b32_e32 v47, v50
	v_mov_b32_e32 v48, v50
	v_mov_b32_e32 v49, v50
	v_mov_b32_e32 v18, v50
	v_mov_b32_e32 v19, v50
	v_mov_b32_e32 v20, v50
	v_mov_b32_e32 v21, v50
	v_mov_b32_e32 v22, v50
	v_mov_b32_e32 v23, v50
	v_mov_b32_e32 v24, v50
	v_mov_b32_e32 v25, v50
	v_mov_b32_e32 v26, v50
	v_mov_b32_e32 v27, v50
	v_mov_b32_e32 v28, v50
	v_mov_b32_e32 v29, v50
	v_mov_b32_e32 v30, v50
	v_mov_b32_e32 v31, v50
	v_mov_b32_e32 v32, v50
	v_mov_b32_e32 v33, v50
	v_mov_b32_e32 v2, v50
	v_mov_b32_e32 v3, v50
	v_mov_b32_e32 v4, v50
	v_mov_b32_e32 v5, v50
	v_mov_b32_e32 v6, v50
	v_mov_b32_e32 v7, v50
	v_mov_b32_e32 v8, v50
	v_mov_b32_e32 v9, v50
	v_mov_b32_e32 v10, v50
	v_mov_b32_e32 v11, v50
	v_mov_b32_e32 v12, v50
	v_mov_b32_e32 v13, v50
	v_mov_b32_e32 v14, v50
	v_mov_b32_e32 v15, v50
	v_mov_b32_e32 v16, v50
	v_mov_b32_e32 v17, v50
	s_waitcnt lgkmcnt(0)
	s_barrier
	ds_read_b128 v[206:209], v203 offset:0
	ds_read_b128 v[210:213], v204 offset:18432
	ds_read_b128 v[214:217], v204 offset:23040
	ds_read_b128 v[218:221], v203 offset:4608
	ds_read_b128 v[222:225], v203 offset:32
	ds_read_b128 v[226:229], v204 offset:18464
	ds_read_b128 v[230:233], v204 offset:23072
	ds_read_b128 v[234:237], v203 offset:4640
	v_subrev_u32_e32 v180, s82, v180
	v_add_u32_e32 v180, v180, v138
	v_subrev_u32_e32 v178, s82, v178
	v_add_u32_e32 v178, v178, v138
	v_subrev_u32_e32 v176, s82, v176
	v_add_u32_e32 v176, v176, v138
	v_subrev_u32_e32 v174, s82, v174
	v_add_u32_e32 v174, v174, v138
	v_subrev_u32_e32 v172, s82, v172
	v_add_u32_e32 v172, v172, v138
	v_subrev_u32_e32 v170, s82, v170
	v_add_u32_e32 v170, v170, v138
	v_subrev_u32_e32 v168, s82, v168
	v_add_u32_e32 v168, v168, v138
	v_subrev_u32_e32 v166, s82, v166
	v_add_u32_e32 v166, v166, v138
	s_add_u32 s84, s82, 0x149c0000
	s_addc_u32 s85, s83, 0
	s_add_u32 s86, s82, 0x9dd0000
	s_addc_u32 s87, s83, 0
	s_and_b64 s[88:89], exec, s[12:13]
	s_cselect_b32 s90, 1, 0
	s_and_b64 s[88:89], exec, s[14:15]
	s_cselect_b32 s91, 1, 0
	s_and_b32 s90, s90, s91
	s_and_b64 s[88:89], exec, s[16:17]
	s_cselect_b32 s91, 1, 0
	s_and_b32 s90, s90, s91
	s_and_b64 s[88:89], exec, s[18:19]
	s_cselect_b32 s91, 1, 0
	s_and_b32 s90, s90, s91
	s_branch .LBB0_3124
